# chain L stage specialised for full 128-row chunks: no validity selects, decay factors side by side, packed V*kd multiplies
# baseline (speedup 1.0000x reference)
; template <bool STORE> __device__ __forceinline__ void ret_chain(LAS unsigned char* lds, int b, int h, bf16* Qb, const bf16* Kb, const bf16* Vb, const bf16* Gb, const f32x2* tab, float* s_out) {
;     ...
;         const int Leff = ci == 0 ? NMETA : 128;
;         const int row_base = ci == 0 ? (R_META + b * NMETA) : (b * SEQ + (ci - 1) * 128);
; #pragma unroll
;         for (int it = 0; it < 4; ++it) {
;             const int item = tid + NTHREADS * it, j = item >> 4, c = item & 15;
;             const bool valid = j < Leff;
;             const float kd = valid ? __expf(lg * (float)(Leff - 1 - j)) : 0.f;
;             const u32x4 q = valid ? rq[it] : zero4u, k = valid ? rk[it] : zero4u, v = rv[it];
.LBB0_319:
	s_cmp_eq_u32 s45, 0
	s_cselect_b64 s[28:29], -1, 0
	s_and_b64 s[30:31], s[28:29], exec
	s_cselect_b32 s48, 16, 0x80
	s_cmp_eq_u32 s45, 0
	s_cbranch_scc1 .Lchain_genL
	v_readlane_b32 s30, v254, 6
	v_not_b32_e32 v84, v215
	v_not_b32_e32 v85, v216
	v_not_b32_e32 v86, v217
	v_not_b32_e32 v87, v218
	v_add_u32_e32 v84, 0x80, v84
	v_add_u32_e32 v85, 0x80, v85
	v_add_u32_e32 v86, 0x80, v86
	v_add_u32_e32 v87, 0x80, v87
	v_cvt_f32_i32_e32 v84, v84
	v_cvt_f32_i32_e32 v85, v85
	v_cvt_f32_i32_e32 v86, v86
	v_cvt_f32_i32_e32 v87, v87
	v_mul_f32_e32 v84, s33, v84
	v_mul_f32_e32 v85, s33, v85
	v_mul_f32_e32 v86, s33, v86
	v_mul_f32_e32 v87, s33, v87
	v_mul_f32_e32 v84, 0x3fb8aa3b, v84
	v_mul_f32_e32 v85, 0x3fb8aa3b, v85
	v_mul_f32_e32 v86, 0x3fb8aa3b, v86
	v_mul_f32_e32 v87, 0x3fb8aa3b, v87
	v_exp_f32_e32 v84, v84
	v_exp_f32_e32 v85, v85
	v_exp_f32_e32 v86, v86
	v_exp_f32_e32 v87, v87
	s_cmp_lt_u32 s45, 0x100
	s_cbranch_scc1 .Lchain_fw0
	s_waitcnt vmcnt(8)
	s_branch .Lchain_fw1

; __device__ __forceinline__ unsigned cvt_pk_bf16(float lo, float hi) { unsigned r; asm volatile("v_cvt_pk_bf16_f32 %0, %1, %2" : "=v"(r) : "v"(lo), "v"(hi)); return r; }
; #define LAS __attribute__((address_space(3)))
; template <bool STORE> __device__ __forceinline__ void ret_chain(LAS unsigned char* lds, int b, int h, bf16* Qb, const bf16* Kb, const bf16* Vb, const bf16* Gb, const f32x2* tab, float* s_out) {
;     ...
; #pragma unroll
;         for (int it = 0; it < 4; ++it) {
;             const int item = tid + NTHREADS * it, j = item >> 4, c = item & 15;
;             const bool valid = j < Leff;
;             const float kd = valid ? __expf(lg * (float)(Leff - 1 - j)) : 0.f;
;             const u32x4 q = valid ? rq[it] : zero4u, k = valid ? rk[it] : zero4u, v = rv[it];
;             u32x4 vs;
; #pragma unroll
;             for (int p = 0; p < 4; ++p) vs[p] = cvt_pk_bf16(bflo(v[p]) * kd, bfhi(v[p]) * kd);
;             const int boff = j * PTB + (8 * c) * 2;
;             *(LAS u32x4*)(lds + RG0 + boff) = q; *(LAS u32x4*)(lds + RG1 + boff) = k; *(LAS u32x4*)(lds + RG2 + boff) = vs;
;         }
.Lchain_fw1:
	ds_write_b128 v196, v[4:7]
	ds_write_b128 v196, v[8:11] offset:34816
	ds_write_b128 v198, v[16:19]
	ds_write_b128 v198, v[20:23] offset:34816
	ds_write_b128 v200, v[28:31]
	ds_write_b128 v200, v[32:35] offset:34816
	ds_write_b128 v202, v[40:43]
	ds_write_b128 v202, v[44:47] offset:34816
	v_lshlrev_b32_e32 v92, 16, v12
	v_and_b32_e32 v93, 0xffff0000, v12
	v_lshlrev_b32_e32 v94, 16, v13
	v_and_b32_e32 v95, 0xffff0000, v13
	v_pk_mul_f32 v[92:93], v[92:93], v[84:85] op_sel_hi:[1,0]
	v_pk_mul_f32 v[94:95], v[94:95], v[84:85] op_sel_hi:[1,0]
	v_cvt_pk_bf16_f32 v88, v92, v93
	v_cvt_pk_bf16_f32 v89, v94, v95
	v_lshlrev_b32_e32 v92, 16, v14
	v_and_b32_e32 v93, 0xffff0000, v14
	v_lshlrev_b32_e32 v94, 16, v15
	v_and_b32_e32 v95, 0xffff0000, v15
	v_pk_mul_f32 v[92:93], v[92:93], v[84:85] op_sel_hi:[1,0]
	v_pk_mul_f32 v[94:95], v[94:95], v[84:85] op_sel_hi:[1,0]
	v_cvt_pk_bf16_f32 v90, v92, v93
	v_cvt_pk_bf16_f32 v91, v94, v95
	v_add_u32_e32 v108, s30, v196
	ds_write_b128 v108, v[88:91]
	v_lshlrev_b32_e32 v92, 16, v24
	v_and_b32_e32 v93, 0xffff0000, v24
	v_lshlrev_b32_e32 v94, 16, v25
	v_and_b32_e32 v95, 0xffff0000, v25
	v_pk_mul_f32 v[92:93], v[92:93], v[84:85] op_sel:[0,1]
	v_pk_mul_f32 v[94:95], v[94:95], v[84:85] op_sel:[0,1]
	v_cvt_pk_bf16_f32 v96, v92, v93
	v_cvt_pk_bf16_f32 v97, v94, v95
	v_lshlrev_b32_e32 v92, 16, v26
	v_and_b32_e32 v93, 0xffff0000, v26
	v_lshlrev_b32_e32 v94, 16, v27
	v_and_b32_e32 v95, 0xffff0000, v27
	v_pk_mul_f32 v[92:93], v[92:93], v[84:85] op_sel:[0,1]
	v_pk_mul_f32 v[94:95], v[94:95], v[84:85] op_sel:[0,1]
	v_cvt_pk_bf16_f32 v98, v92, v93
	v_cvt_pk_bf16_f32 v99, v94, v95
	v_add_u32_e32 v109, s30, v198
	ds_write_b128 v109, v[96:99]
	v_lshlrev_b32_e32 v92, 16, v36
	v_and_b32_e32 v93, 0xffff0000, v36
	v_lshlrev_b32_e32 v94, 16, v37
	v_and_b32_e32 v95, 0xffff0000, v37
	v_pk_mul_f32 v[92:93], v[92:93], v[86:87] op_sel_hi:[1,0]
	v_pk_mul_f32 v[94:95], v[94:95], v[86:87] op_sel_hi:[1,0]
	v_cvt_pk_bf16_f32 v100, v92, v93
	v_cvt_pk_bf16_f32 v101, v94, v95
	v_lshlrev_b32_e32 v92, 16, v38
	v_and_b32_e32 v93, 0xffff0000, v38
	v_lshlrev_b32_e32 v94, 16, v39
	v_and_b32_e32 v95, 0xffff0000, v39
	v_pk_mul_f32 v[92:93], v[92:93], v[86:87] op_sel_hi:[1,0]
	v_pk_mul_f32 v[94:95], v[94:95], v[86:87] op_sel_hi:[1,0]
	v_cvt_pk_bf16_f32 v102, v92, v93
	v_cvt_pk_bf16_f32 v103, v94, v95
	v_add_u32_e32 v110, s30, v200
	ds_write_b128 v110, v[100:103]
	v_lshlrev_b32_e32 v92, 16, v48
	v_and_b32_e32 v93, 0xffff0000, v48
	v_lshlrev_b32_e32 v94, 16, v49
	v_and_b32_e32 v95, 0xffff0000, v49
	v_pk_mul_f32 v[92:93], v[92:93], v[86:87] op_sel:[0,1]
	v_pk_mul_f32 v[94:95], v[94:95], v[86:87] op_sel:[0,1]
	v_cvt_pk_bf16_f32 v104, v92, v93
	v_cvt_pk_bf16_f32 v105, v94, v95
	v_lshlrev_b32_e32 v92, 16, v50
	v_and_b32_e32 v93, 0xffff0000, v50
	v_lshlrev_b32_e32 v94, 16, v51
	v_and_b32_e32 v95, 0xffff0000, v51
	v_pk_mul_f32 v[92:93], v[92:93], v[86:87] op_sel:[0,1]
	v_pk_mul_f32 v[94:95], v[94:95], v[86:87] op_sel:[0,1]
	v_cvt_pk_bf16_f32 v106, v92, v93
	v_cvt_pk_bf16_f32 v107, v94, v95
	v_add_u32_e32 v111, s30, v202
	ds_write_b128 v111, v[104:107]
	s_branch .Lchain_Ldone
.Lchain_genL:
	v_not_b32_e32 v84, v215
	v_add_u32_e32 v84, s48, v84
	v_cvt_f32_i32_e32 v84, v84
	v_cmp_gt_i32_e32 vcc, s48, v215
	s_cmp_lt_u32 s45, 0x100
	s_cbranch_scc1 .Lchain_w0
	s_waitcnt vmcnt(8)
	s_branch .Lchain_w1

; #define CHAIN_BAR() do { asm volatile("s_waitcnt lgkmcnt(0)" ::: "memory"); __builtin_amdgcn_s_barrier(); asm volatile("" ::: "memory"); } while (0)
; template <bool STORE> __device__ __forceinline__ void ret_chain(LAS unsigned char* lds, int b, int h, bf16* Qb, const bf16* Kb, const bf16* Vb, const bf16* Gb, const f32x2* tab, float* s_out) {
;     ...
;         CHAIN_BAR();
;         if (ci + 1 < 17) CHAIN_LOAD(ci + 1);
.Lchain_Ldone:
	s_waitcnt lgkmcnt(0)
	s_barrier
	s_cmpk_eq_i32 s45, 0x800
	s_cbranch_scc1 .LBB0_321
	v_add_u32_e32 v4, s45, v240
	v_add_u32_e32 v14, s45, v239
	v_add_u32_e32 v28, s45, v238
	v_add_u32_e32 v38, s45, v237
	v_ashrrev_i32_e32 v5, 31, v4
	v_ashrrev_i32_e32 v15, 31, v14
	v_ashrrev_i32_e32 v29, 31, v28
	v_ashrrev_i32_e32 v39, 31, v38
	v_lshlrev_b64 v[12:13], 11, v[4:5]
	v_lshlrev_b64 v[20:21], 11, v[14:15]
	v_lshlrev_b64 v[36:37], 11, v[28:29]
	v_lshlrev_b64 v[44:45], 11, v[38:39]
	v_or_b32_e32 v12, v12, v241
	v_or_b32_e32 v20, v20, v241
	v_or_b32_e32 v36, v36, v241
	v_or_b32_e32 v44, v44, v241
	v_lshl_add_u64 v[4:5], s[2:3], 0, v[12:13]
	v_lshl_add_u64 v[8:9], s[40:41], 0, v[12:13]
	v_lshl_add_u64 v[12:13], s[42:43], 0, v[12:13]
	v_lshl_add_u64 v[16:17], s[2:3], 0, v[20:21]
	v_lshl_add_u64 v[22:23], s[40:41], 0, v[20:21]
	v_lshl_add_u64 v[24:25], s[42:43], 0, v[20:21]
	v_lshl_add_u64 v[28:29], s[2:3], 0, v[36:37]
	v_lshl_add_u64 v[32:33], s[40:41], 0, v[36:37]
	v_lshl_add_u64 v[36:37], s[42:43], 0, v[36:37]
	v_lshl_add_u64 v[40:41], s[2:3], 0, v[44:45]
	v_lshl_add_u64 v[46:47], s[40:41], 0, v[44:45]
	v_lshl_add_u64 v[48:49], s[42:43], 0, v[44:45]
	global_load_dwordx4 v[4:7], v[4:5], off
	s_nop 0
	global_load_dwordx4 v[8:11], v[8:9], off
	s_nop 0
	global_load_dwordx4 v[12:15], v[12:13], off
	s_nop 0
	global_load_dwordx4 v[16:19], v[16:17], off
	s_nop 0
	global_load_dwordx4 v[20:23], v[22:23], off
	s_nop 0
	global_load_dwordx4 v[24:27], v[24:25], off
	s_nop 0
	global_load_dwordx4 v[28:31], v[28:29], off
	s_nop 0
	global_load_dwordx4 v[32:35], v[32:33], off
	s_nop 0
	global_load_dwordx4 v[36:39], v[36:37], off
	s_nop 0
	global_load_dwordx4 v[40:43], v[40:41], off
	s_nop 0
	global_load_dwordx4 v[44:47], v[46:47], off
	s_nop 0
	global_load_dwordx4 v[48:51], v[48:49], off
